# early partial L2 writeback by the 1st and 17th local arriver at seams 0 and 4 (shorten the leader's flush)
# baseline (speedup 1.0000x reference)
.LBB0_61:
	s_or_b64 exec, exec, s[10:11]
	v_cvt_f32_u32_e32 v4, v2
	s_waitcnt vmcnt(0)
	v_readfirstlane_b32 s3, v3
	s_nop 3
	s_and_b32 s98, s3, 15
	s_cmp_lg_u32 s98, 0
	s_cbranch_scc1 .Lew0
	buffer_wbl2 sc1
.Lew0:
	v_sub_u32_e32 v3, 0, v2
	v_rcp_iflag_f32_e32 v4, v4
	v_add_u32_e32 v5, s3, v1
	v_mul_f32_e32 v4, 0x4f7ffffe, v4
	v_cvt_u32_f32_e32 v4, v4
	v_mul_lo_u32 v1, v3, v4
	v_mul_hi_u32 v1, v4, v1
	v_add_u32_e32 v1, v4, v1
	v_mul_hi_u32 v1, v5, v1
	v_mul_lo_u32 v3, v1, v2
	v_sub_u32_e32 v3, v5, v3
	v_add_u32_e32 v4, 1, v1
	v_cmp_ge_u32_e32 vcc, v3, v2
	s_nop 1
	v_cndmask_b32_e32 v1, v1, v4, vcc
	v_sub_u32_e32 v4, v3, v2
	v_cndmask_b32_e32 v3, v3, v4, vcc
	v_add_u32_e32 v4, 1, v1
	v_cmp_ge_u32_e32 vcc, v3, v2
	v_add_u32_e32 v3, 1, v5
	s_nop 0
	v_cndmask_b32_e32 v1, v1, v4, vcc
	v_mul_lo_u32 v4, v2, v1
	v_add_u32_e32 v2, v4, v2
	v_cmp_ne_u32_e32 vcc, v3, v2
	s_and_saveexec_b64 s[8:9], vcc
	s_xor_b64 s[8:9], exec, s[8:9]
	s_cbranch_execz .LBB0_75
	s_waitcnt lgkmcnt(0)
	v_mov_b32_e32 v0, 0x2000
	global_load_dword v0, v0, s[6:7] offset:1024 sc1
	s_add_u32 s44, s6, 0x2400
	s_addc_u32 s45, s7, 0
	s_waitcnt vmcnt(0)
	v_cmp_eq_u32_e32 vcc, v0, v1
	s_and_saveexec_b64 s[38:39], vcc
	s_cbranch_execz .LBB0_74
	s_add_u32 s40, s30, 0xfc00200
	s_addc_u32 s41, s31, 0
	s_mov_b32 s3, 1
	s_mov_b64 s[60:61], 0
	v_mov_b32_e32 v0, 0
	s_branch .LBB0_65

.LBB0_782:
	s_mov_b32 s101, 0
	s_cmp_gt_i32 s69, 5
	s_cselect_b64 s[0:1], -1, 0
	s_and_b64 s[2:3], s[18:19], s[0:1]
	s_andn2_b64 vcc, exec, s[2:3]
	s_cbranch_vccnz .LBB0_836
	v_mov_b32_e32 v0, 0x20040
	ds_read_b32 v1, v0 offset:16
	ds_read_b32 v3, v0 offset:8
	s_waitcnt lgkmcnt(0)
	v_readfirstlane_b32 s6, v1
	s_nop 3
	s_cmp_eq_u32 s6, 0
	s_cbranch_scc1 .Ls4_orig
	s_waitcnt vmcnt(0)
	s_barrier
	v_cmp_gt_u32_e32 vcc, 64, v199
	s_cbranch_vccz .Ls4_done
	s_lshl_b32 s6, s33, 8
	s_add_u32 s6, s92, s6
	s_addc_u32 s7, s93, 0
	v_mov_b32_e32 v0, 0x1400
	v_mov_b32_e32 v1, 1
	s_lshl_b32 s10, s33, 7
	s_add_u32 s10, s10, 0x3a00
	v_lshl_add_u32 v4, v199, 2, s10
	v_lshl_add_u32 v3, v3, 2, s10
	v_cmp_eq_u32_e32 vcc, 0, v199
	s_and_saveexec_b64 s[12:13], vcc
	global_store_dword v3, v1, s[92:93]
	global_atomic_add v2, v0, v1, s[6:7] sc0
	s_mov_b64 exec, s[12:13]
	s_waitcnt vmcnt(0)
	v_readfirstlane_b32 s11, v2
	s_nop 3
	s_lshr_b32 s101, s11, 5
	s_add_i32 s101, s101, 1
	s_and_b32 s11, s11, 31
	s_and_b32 s14, s11, 15
	s_cmp_lg_u32 s14, 0
	s_cbranch_scc1 .Ls4_noearly
	buffer_wbl2 sc1
.Ls4_noearly:
	s_cmp_eq_u32 s11, 31
	s_cbranch_scc0 .Ls4_wait
	buffer_wbl2 sc1
	s_waitcnt vmcnt(0)
	v_mov_b32_e32 v0, 0xfc03000
	s_and_saveexec_b64 s[12:13], vcc
	global_atomic_add v2, v0, v1, s[30:31] offset:1024 sc0
	s_mov_b64 exec, s[12:13]
	s_waitcnt vmcnt(0)
	v_readfirstlane_b32 s11, v2
	s_nop 3
	s_and_b32 s11, s11, 7
	s_cmp_eq_u32 s11, 7
	s_cbranch_scc0 .Ls4_wait
	v_mov_b32_e32 v0, 0xfc03500
	s_and_saveexec_b64 s[12:13], vcc
	global_atomic_add v0, v1, s[30:31]
	s_mov_b64 exec, s[12:13]
